# gate/up and down GEMMs: next-tile index arithmetic in closed form (no division emulation) on top of the down-GEMM reversal
# speedup vs baseline: 1.0068x; 1.0068x over previous
.LBB0_1791:
	s_add_i32 s71, s71, 1
	s_mul_i32 s3, s71, s70
	s_mul_hi_u32 s24, s71, s19
	s_add_i32 s3, s24, s3
	s_mul_i32 s24, s71, s19
	s_add_u32 s24, s24, s2
	s_addc_u32 s25, s3, s73
	v_mov_b64_e32 v[0:1], 0x2800
	v_cmp_lt_i64_e64 s[38:39], s[24:25], v[0:1]
	v_mov_b64_e32 v[0:1], 0x27ff
	v_cmp_gt_i64_e64 s[40:41], s[24:25], v[0:1]
	s_and_b64 vcc, exec, s[40:41]
	s_cbranch_vccnz .LBB0_1800
	s_and_b32 s3, s24, 7
	s_lshr_b32 s59, s24, 3
	s_mul_i32 s3, s3, 0x500
	s_add_i32 s3, s3, s59
	s_bfe_u32 s58, s3, 0x40003
	s_lshr_b32 s59, s3, 7
	s_lshl_b32 s59, s59, 3
	s_and_b32 s3, s3, 7
	s_add_i32 s60, s59, s3
	s_andn2_b64 vcc, exec, s[40:41]
	s_mov_b64 s[24:25], -1
	s_cbranch_vccz .LBB0_1801

.LBB0_1862:
	s_add_i32 s74, s74, 1
	s_mul_i32 s3, s74, s71
	s_mul_hi_u32 s36, s74, s19
	s_add_i32 s3, s36, s3
	s_mul_i32 s36, s74, s19
	s_add_u32 s36, s36, s2
	s_addc_u32 s37, s3, s73
	v_mov_b64_e32 v[0:1], 0xa00
	v_cmp_lt_i64_e64 s[40:41], s[36:37], v[0:1]
	v_mov_b64_e32 v[0:1], 0x9ff
	v_cmp_gt_i64_e32 vcc, s[36:37], v[0:1]
	s_cbranch_vccnz .LBB0_1864
	s_and_b32 s3, s36, 7
	s_lshr_b32 s59, s36, 3
	s_mul_i32 s3, s3, 0x140
	s_add_i32 s3, s3, s59
	s_bfe_u32 s58, s3, 0x20003
	s_lshr_b32 s59, s3, 5
	s_lshl_b32 s59, s59, 3
	s_and_b32 s3, s3, 7
	s_add_i32 s60, s59, s3
	s_mul_i32 s98, s60, 0xcccd
	s_lshr_b32 s98, s98, 22
	s_mul_i32 s98, s98, 0xa0
	s_addk_i32 s98, 0x4f
	s_sub_i32 s60, s98, s60
